# also counted waits for the P3 epilogue's first gate-load batch and the band attention item start waits only for Q
# speedup vs baseline: 1.0079x; 1.0034x over previous
; #define LAS __attribute__((address_space(3)))
; __device__ __forceinline__ float fast_exp2(float x) { return __builtin_amdgcn_exp2f(x); }
; template <bool WIN>
; __device__ __forceinline__ void attn_item(bf16_t* U, const float* sink, int ci, int h, LAS unsigned char* wl, const LAS float* tbl, int lane_in) {
;     ...
;     const int smin = 2 * tmin;
;     asm volatile("s_waitcnt lgkmcnt(0)" ::: "memory");
;     ATT_DMA(smin); ATT_DMA(smin + 1);
;     bf16x8 qr[2][4];
; #pragma unroll
;     for (int qh = 0; qh < 2; ++qh)
; #pragma unroll
;         for (int d0 = 0; d0 < 4; ++d0) qr[qh][d0] = *(const bf16x8*)(U + (size_t)(row0 + 32 * qh + r32) * LDU + qcol + 16 * d0 + 8 * hi);
;     u32x2 zr[2][2][4];
; #pragma unroll
;     for (int qh = 0; qh < 2; ++qh)
; #pragma unroll
;         for (int dh = 0; dh < 2; ++dh)
; #pragma unroll
;             for (int g = 0; g < 4; ++g) zr[qh][dh][g] = *(const u32x2*)(U + (size_t)(row0 + 32 * qh + r32) * LDU + 4 * hi + zcol + 32 * dh + 8 * g);
;     f32x16 o[2][2];
; #pragma unroll
;     for (int a = 0; a < 2; ++a)
; #pragma unroll
;         for (int b = 0; b < 2; ++b)
; #pragma unroll
;             for (int r = 0; r < 16; ++r) o[a][b][r] = 0.f;
;     float lrun[2];
;     const float slope2 = WIN ? (LOG2E * __builtin_amdgcn_exp2f(-(float)(h + 1))) : 0.f;
;     if (WIN) { lrun[0] = hi == 0 ? fast_exp2(sink[h] * LOG2E) : 0.f; lrun[1] = lrun[0]; }
;     else { lrun[0] = 0.f; lrun[1] = 0.f; }
;     const LAS float* th = tbl + h * 257;
;     int kfo[4];
; #pragma unroll
;     for (int d0 = 0; d0 < 4; ++d0) kfo[d0] = r32 * 128 + (((2 * d0 + hi) ^ ((r32 >> 1) & 7)) * 16);
;     const int vfo = 4096 + ((lane >> 4) & 1) * 32 + (lane & 3) * 8 + (4 * hi + ((lane & 15) >> 2)) * 64;
.LBB0_614:
	s_add_i32 s7, s7, 32
	s_mul_hi_i32 s11, s7, 0x2a00
	s_mulk_i32 s7, 0x2a00
	s_add_u32 s10, s82, s7
	s_addc_u32 s11, s83, s11
	s_mov_b32 m0, s31
	v_lshl_add_u64 v[6:7], v[146:147], 1, s[10:11]
	global_load_lds_dwordx4 v[6:7], off
	v_lshl_add_u64 v[6:7], v[166:167], 1, s[10:11]
	s_mov_b32 m0, s34
	v_lshl_add_u64 v[8:9], v[176:177], 1, s[10:11]
	global_load_lds_dwordx4 v[6:7], off
	v_lshl_add_u64 v[6:7], v[168:169], 1, s[10:11]
	s_mov_b32 m0, s35
	v_ashrrev_i32_e32 v4, 5, v2
	global_load_lds_dwordx4 v[6:7], off
	v_lshl_add_u64 v[6:7], v[170:171], 1, s[10:11]
	s_mov_b32 m0, s46
	v_ashrrev_i32_e32 v5, 31, v4
	global_load_lds_dwordx4 v[6:7], off
	v_lshl_add_u64 v[6:7], v[174:175], 1, s[10:11]
	s_mov_b32 m0, s47
	v_and_b32_e32 v10, 31, v2
	global_load_lds_dwordx4 v[6:7], off
	s_mov_b32 m0, s90
	v_lshl_add_u64 v[6:7], v[6:7], 0, 64
	global_load_lds_dwordx4 v[8:9], off
	s_mov_b32 m0, s91
	v_add_u32_e32 v11, s36, v10
	global_load_lds_dwordx4 v[6:7], off
	v_lshl_add_u64 v[6:7], v[8:9], 0, 64
	s_mov_b32 m0, s92
	v_lshlrev_b64 v[8:9], 3, v[4:5]
	global_load_lds_dwordx4 v[6:7], off
	v_lshlrev_b32_e32 v6, 3, v4
	v_ashrrev_i32_e32 v7, 31, v6
	v_sub_co_u32_e32 v8, vcc, 0, v8
	v_lshl_add_u64 v[6:7], v[6:7], 1, s[0:1]
	v_add_u32_e32 v12, 32, v11
	v_subb_co_u32_e32 v9, vcc, 0, v9, vcc
	v_mad_i64_i32 v[172:173], s[10:11], v11, s19, v[6:7]
	v_mad_i64_i32 v[148:149], s[10:11], v12, s19, v[6:7]
	v_lshl_add_u64 v[6:7], v[6:7], 0, v[8:9]
	v_mad_i64_i32 v[8:9], s[10:11], v11, s19, v[6:7]
	v_add_co_u32_e32 v8, vcc, s20, v8
	v_mad_i64_i32 v[6:7], s[10:11], v12, s19, v[6:7]
	s_nop 0
	v_addc_co_u32_e32 v9, vcc, 0, v9, vcc
	v_add_co_u32_e32 v6, vcc, s20, v6
	global_load_dwordx4 v[98:101], v[172:173], off offset:2560
	global_load_dwordx4 v[102:105], v[172:173], off offset:2592
	global_load_dwordx4 v[106:109], v[172:173], off offset:2624
	global_load_dwordx4 v[110:113], v[172:173], off offset:2656
	v_addc_co_u32_e32 v7, vcc, 0, v7, vcc
	global_load_dwordx4 v[114:117], v[148:149], off offset:2560
	global_load_dwordx4 v[118:121], v[148:149], off offset:2592
	global_load_dwordx4 v[122:125], v[148:149], off offset:2624
	global_load_dwordx4 v[126:129], v[148:149], off offset:2656
	global_load_dwordx2 v[198:199], v[8:9], off offset:1536
	global_load_dwordx2 v[192:193], v[8:9], off offset:1552
	global_load_dwordx2 v[190:191], v[8:9], off offset:1568
	global_load_dwordx2 v[188:189], v[8:9], off offset:1584
	global_load_dwordx2 v[186:187], v[8:9], off offset:1600
	global_load_dwordx2 v[182:183], v[8:9], off offset:1616
	global_load_dwordx2 v[180:181], v[8:9], off offset:1632
	global_load_dwordx2 v[178:179], v[8:9], off offset:1648
	global_load_dwordx2 v[164:165], v[6:7], off offset:1536
	global_load_dwordx2 v[162:163], v[6:7], off offset:1552
	global_load_dwordx2 v[160:161], v[6:7], off offset:1568
	global_load_dwordx2 v[158:159], v[6:7], off offset:1584
	global_load_dwordx2 v[156:157], v[6:7], off offset:1600
	global_load_dwordx2 v[154:155], v[6:7], off offset:1616
	global_load_dwordx2 v[152:153], v[6:7], off offset:1632
	global_load_dwordx2 v[150:151], v[6:7], off offset:1648
	v_lshrrev_b32_e32 v5, 1, v2
	v_bitop3_b32 v6, v5, v4, 7 bitop3:0x6c
	v_lshlrev_b32_e32 v201, 4, v6
	v_add_u32_e32 v6, 2, v4
	v_bitop3_b32 v6, v6, v5, 7 bitop3:0x78
	v_lshlrev_b32_e32 v13, 2, v4
	v_lshlrev_b32_e32 v202, 4, v6
	v_add_u32_e32 v6, 4, v4
	v_add_u32_e32 v4, 6, v4
	v_lshlrev_b32_e32 v2, 1, v2
	v_bitop3_b32 v6, v6, v5, 7 bitop3:0x78
	v_bitop3_b32 v4, v4, v5, 7 bitop3:0x78
	v_and_b32_e32 v205, 32, v2
	v_and_or_b32 v2, v3, 3, v13
	s_add_i32 s11, s6, 64
	s_lshl_b32 s6, s21, 5
	v_mov_b32_e32 v50, 0
	v_lshlrev_b32_e32 v200, 7, v10
	v_lshlrev_b32_e32 v203, 4, v6
	v_lshlrev_b32_e32 v204, 4, v4
	v_lshlrev_b32_e32 v206, 6, v2
	s_add_i32 s10, s36, 0xfffffe00
	v_sub_u32_e32 v207, v10, v13
	s_sub_i32 s36, 0, s6
	s_lshl_b32 s37, s21, 13
	v_mov_b32_e32 v51, v50
	v_mov_b32_e32 v52, v50
	v_mov_b32_e32 v53, v50
	v_mov_b32_e32 v54, v50
	v_mov_b32_e32 v55, v50
	v_mov_b32_e32 v56, v50
	v_mov_b32_e32 v57, v50
	v_mov_b32_e32 v58, v50
	v_mov_b32_e32 v59, v50
	v_mov_b32_e32 v60, v50
	v_mov_b32_e32 v61, v50
	v_mov_b32_e32 v62, v50
	v_mov_b32_e32 v63, v50
	v_mov_b32_e32 v64, v50
	v_mov_b32_e32 v65, v50
	v_mov_b32_e32 v34, v50
	v_mov_b32_e32 v35, v50
	v_mov_b32_e32 v36, v50
	v_mov_b32_e32 v37, v50
	v_mov_b32_e32 v38, v50
	v_mov_b32_e32 v39, v50
	v_mov_b32_e32 v40, v50
	v_mov_b32_e32 v41, v50
	v_mov_b32_e32 v42, v50
	v_mov_b32_e32 v43, v50
	v_mov_b32_e32 v44, v50
	v_mov_b32_e32 v45, v50
	v_mov_b32_e32 v46, v50
	v_mov_b32_e32 v47, v50
	v_mov_b32_e32 v48, v50
	v_mov_b32_e32 v49, v50
	v_mov_b32_e32 v18, v50
	v_mov_b32_e32 v19, v50
	v_mov_b32_e32 v20, v50
	v_mov_b32_e32 v21, v50
	v_mov_b32_e32 v22, v50
	v_mov_b32_e32 v23, v50
	v_mov_b32_e32 v24, v50
	v_mov_b32_e32 v25, v50
	v_mov_b32_e32 v26, v50
	v_mov_b32_e32 v27, v50
	v_mov_b32_e32 v28, v50
	v_mov_b32_e32 v29, v50
	v_mov_b32_e32 v30, v50
	v_mov_b32_e32 v31, v50
	v_mov_b32_e32 v32, v50
	v_mov_b32_e32 v33, v50
	v_mov_b32_e32 v2, v50
	v_mov_b32_e32 v3, v50
	v_mov_b32_e32 v4, v50
	v_mov_b32_e32 v5, v50
	v_mov_b32_e32 v6, v50
	v_mov_b32_e32 v7, v50
	v_mov_b32_e32 v8, v50
	v_mov_b32_e32 v9, v50
	v_mov_b32_e32 v10, v50
	v_mov_b32_e32 v11, v50
	v_mov_b32_e32 v12, v50
	v_mov_b32_e32 v13, v50
	v_mov_b32_e32 v14, v50
	v_mov_b32_e32 v15, v50
	v_mov_b32_e32 v16, v50
	v_mov_b32_e32 v17, v50
	v_mov_b32_e32 v184, v50
	v_mov_b32_e32 v185, v50
	v_lshlrev_b32_e32 v212, 1, v146
	v_lshlrev_b32_e32 v213, 1, v166
	v_lshlrev_b32_e32 v214, 1, v168
	v_lshlrev_b32_e32 v215, 1, v170
	v_lshlrev_b32_e32 v216, 1, v174
	v_lshlrev_b32_e32 v217, 1, v176
	v_lshl_add_u32 v218, v174, 1, 64
	v_lshl_add_u32 v219, v176, 1, 64
	s_waitcnt vmcnt(16)
	s_branch .LBB0_616

; __device__ __forceinline__ unsigned cvt_pk_bf16(float lo, float hi) { const f32x2_t v = {lo, hi}; const bf16x2_t b = __builtin_convertvector(v, bf16x2_t); return __builtin_bit_cast(unsigned, b); }
; __device__ __forceinline__ float bf_lo(unsigned w) { return __uint_as_float(w << 16); }
; __device__ __forceinline__ float bf_hi(unsigned w) { return __uint_as_float(w & 0xffff0000u); }
; __device__ __forceinline__ float fast_rcp(float x) { return __builtin_amdgcn_rcpf(x); }
;     __device__ __forceinline__ void operator()(f32x4 (&acc)[2][2][4][2], const Unit& u, int wr, int wc, int fr, int fq) const {
;     ...
;             for (int m = 0; m < 4; ++m) {
;                 const int r = EPI_ROWS(ai, m);
; #pragma unroll
;                 for (int bj = 0; bj < 2; ++bj) {
;                     if (u.seg == 0) {
; #pragma unroll
;                         for (int q = 0; q < 4; ++q) {
;                             const float r0 = bf_lo(ga[m][bj][q]) * fast_rcp(bf_lo(gb[m][bj][q])), r1 = bf_hi(ga[m][bj][q]) * fast_rcp(bf_hi(gb[m][bj][q]));
;                             acc[ai][bj][m][q >> 1][(q & 1) * 2] *= r0; acc[ai][bj][m][q >> 1][(q & 1) * 2 + 1] *= r1;
;                         }
;                     } else {
;                         u32x4 w;
; #pragma unroll
;                         for (int q = 0; q < 4; ++q) {
;                             const float a0 = acc[ai][bj][m][q >> 1][(q & 1) * 2] * bf_lo(gb[m][bj][q]), a1 = acc[ai][bj][m][q >> 1][(q & 1) * 2 + 1] * bf_hi(gb[m][bj][q]);
;                             w[q] = cvt_pk_bf16(a0, a1);
;                         }
;                         *(u32x4*)(Mg + (size_t)r * DM + c0 + 32 * bj) = w;
;                     }
;                 }
.LBB0_738:
	v_lshlrev_b64 v[216:217], 11, v[214:215]
	v_cndmask_b32_e64 v215, 0, 1, s[0:1]
	v_lshl_add_u64 v[230:231], s[80:81], 0, v[216:217]
	s_mov_b64 s[14:15], -1
	v_cmp_ne_u32_e64 s[42:43], 1, v215
	s_andn2_b64 vcc, exec, s[0:1]
	s_waitcnt vmcnt(7)
	v_lshlrev_b32_e32 v220, 16, v190
	v_and_b32_e32 v221, 0xffff0000, v190
	v_lshlrev_b32_e32 v218, 16, v191
	v_and_b32_e32 v219, 0xffff0000, v191
	v_lshlrev_b32_e32 v216, 16, v192
	v_and_b32_e32 v217, 0xffff0000, v192
	v_lshlrev_b32_e32 v192, 16, v193
	v_and_b32_e32 v193, 0xffff0000, v193
	v_lshl_add_u64 v[190:191], v[212:213], 1, v[230:231]
	s_cbranch_vccnz .LBB0_740
	v_pk_mul_f32 v[230:231], v[126:127], v[220:221]
	v_pk_mul_f32 v[232:233], v[128:129], v[218:219]
	v_cvt_pk_bf16_f32 v230, v230, v231
	v_cvt_pk_bf16_f32 v231, v232, v233
	v_pk_mul_f32 v[232:233], v[122:123], v[216:217]
	v_pk_mul_f32 v[234:235], v[124:125], v[192:193]
	v_cvt_pk_bf16_f32 v232, v232, v233
	v_cvt_pk_bf16_f32 v233, v234, v235
	s_mov_b64 s[14:15], 0
	global_store_dwordx4 v[190:191], v[230:233], off

; __device__ __forceinline__ unsigned cvt_pk_bf16(float lo, float hi) { const f32x2_t v = {lo, hi}; const bf16x2_t b = __builtin_convertvector(v, bf16x2_t); return __builtin_bit_cast(unsigned, b); }
; __device__ __forceinline__ float bf_lo(unsigned w) { return __uint_as_float(w << 16); }
; __device__ __forceinline__ float bf_hi(unsigned w) { return __uint_as_float(w & 0xffff0000u); }
; __device__ __forceinline__ float fast_rcp(float x) { return __builtin_amdgcn_rcpf(x); }
;     __device__ __forceinline__ void operator()(f32x4 (&acc)[2][2][4][2], const Unit& u, int wr, int wc, int fr, int fq) const {
;     ...
;             for (int m = 0; m < 4; ++m) {
;                 const int r = EPI_ROWS(ai, m);
; #pragma unroll
;                 for (int bj = 0; bj < 2; ++bj) {
;                     if (u.seg == 0) {
; #pragma unroll
;                         for (int q = 0; q < 4; ++q) {
;                             const float r0 = bf_lo(ga[m][bj][q]) * fast_rcp(bf_lo(gb[m][bj][q])), r1 = bf_hi(ga[m][bj][q]) * fast_rcp(bf_hi(gb[m][bj][q]));
;                             acc[ai][bj][m][q >> 1][(q & 1) * 2] *= r0; acc[ai][bj][m][q >> 1][(q & 1) * 2 + 1] *= r1;
;                         }
;                     } else {
;                         u32x4 w;
; #pragma unroll
;                         for (int q = 0; q < 4; ++q) {
;                             const float a0 = acc[ai][bj][m][q >> 1][(q & 1) * 2] * bf_lo(gb[m][bj][q]), a1 = acc[ai][bj][m][q >> 1][(q & 1) * 2 + 1] * bf_hi(gb[m][bj][q]);
;                             w[q] = cvt_pk_bf16(a0, a1);
;                         }
;                         *(u32x4*)(Mg + (size_t)r * DM + c0 + 32 * bj) = w;
;                     }
;                 }
.LBB0_742:
	s_mov_b64 s[0:1], -1
	s_and_b64 vcc, exec, s[42:43]
	s_waitcnt vmcnt(6)
	v_lshlrev_b32_e32 v218, 16, v186
	v_and_b32_e32 v219, 0xffff0000, v186
	v_lshlrev_b32_e32 v216, 16, v187
	v_and_b32_e32 v217, 0xffff0000, v187
	v_lshlrev_b32_e32 v192, 16, v188
	v_and_b32_e32 v193, 0xffff0000, v188
	v_lshlrev_b32_e32 v186, 16, v189
	v_and_b32_e32 v187, 0xffff0000, v189
	s_cbranch_vccnz .LBB0_744
	v_pk_mul_f32 v[188:189], v[94:95], v[218:219]
	s_mov_b64 s[0:1], 0
	v_cvt_pk_bf16_f32 v230, v188, v189
	v_pk_mul_f32 v[188:189], v[96:97], v[216:217]
	s_nop 0
	v_cvt_pk_bf16_f32 v231, v188, v189
	v_pk_mul_f32 v[188:189], v[90:91], v[192:193]
	s_nop 0
	v_cvt_pk_bf16_f32 v232, v188, v189
	v_pk_mul_f32 v[188:189], v[92:93], v[186:187]
	s_nop 0
	v_cvt_pk_bf16_f32 v233, v188, v189
	global_store_dwordx4 v[190:191], v[230:233], off offset:64

; __device__ __forceinline__ unsigned cvt_pk_bf16(float lo, float hi) { const f32x2_t v = {lo, hi}; const bf16x2_t b = __builtin_convertvector(v, bf16x2_t); return __builtin_bit_cast(unsigned, b); }
; __device__ __forceinline__ float bf_lo(unsigned w) { return __uint_as_float(w << 16); }
; __device__ __forceinline__ float bf_hi(unsigned w) { return __uint_as_float(w & 0xffff0000u); }
; __device__ __forceinline__ float fast_rcp(float x) { return __builtin_amdgcn_rcpf(x); }
;     __device__ __forceinline__ void operator()(f32x4 (&acc)[2][2][4][2], const Unit& u, int wr, int wc, int fr, int fq) const {
;     ...
;             for (int m = 0; m < 4; ++m) {
;                 const int r = EPI_ROWS(ai, m);
; #pragma unroll
;                 for (int bj = 0; bj < 2; ++bj) {
;                     if (u.seg == 0) {
; #pragma unroll
;                         for (int q = 0; q < 4; ++q) {
;                             const float r0 = bf_lo(ga[m][bj][q]) * fast_rcp(bf_lo(gb[m][bj][q])), r1 = bf_hi(ga[m][bj][q]) * fast_rcp(bf_hi(gb[m][bj][q]));
;                             acc[ai][bj][m][q >> 1][(q & 1) * 2] *= r0; acc[ai][bj][m][q >> 1][(q & 1) * 2 + 1] *= r1;
;                         }
;                     } else {
;                         u32x4 w;
; #pragma unroll
;                         for (int q = 0; q < 4; ++q) {
;                             const float a0 = acc[ai][bj][m][q >> 1][(q & 1) * 2] * bf_lo(gb[m][bj][q]), a1 = acc[ai][bj][m][q >> 1][(q & 1) * 2 + 1] * bf_hi(gb[m][bj][q]);
;                             w[q] = cvt_pk_bf16(a0, a1);
;                         }
;                         *(u32x4*)(Mg + (size_t)r * DM + c0 + 32 * bj) = w;
;                     }
;                 }
.LBB0_746:
	v_add_u32_e32 v186, s2, v223
	v_ashrrev_i32_e32 v187, 31, v186
	v_lshlrev_b64 v[186:187], 11, v[186:187]
	v_lshl_add_u64 v[192:193], s[80:81], 0, v[186:187]
	s_mov_b64 s[0:1], -1
	s_and_b64 vcc, exec, s[42:43]
	s_waitcnt vmcnt(5)
	v_lshlrev_b32_e32 v190, 16, v182
	v_and_b32_e32 v191, 0xffff0000, v182
	v_lshlrev_b32_e32 v188, 16, v183
	v_and_b32_e32 v189, 0xffff0000, v183
	v_lshlrev_b32_e32 v186, 16, v184
	v_and_b32_e32 v187, 0xffff0000, v184
	v_lshlrev_b32_e32 v184, 16, v185
	v_and_b32_e32 v185, 0xffff0000, v185
	v_lshl_add_u64 v[182:183], v[212:213], 1, v[192:193]
	s_cbranch_vccnz .LBB0_748
	v_pk_mul_f32 v[192:193], v[118:119], v[190:191]
	s_mov_b64 s[0:1], 0
	v_cvt_pk_bf16_f32 v216, v192, v193
	v_pk_mul_f32 v[192:193], v[120:121], v[188:189]
	s_nop 0
	v_cvt_pk_bf16_f32 v217, v192, v193
	v_pk_mul_f32 v[192:193], v[114:115], v[186:187]
	s_nop 0
	v_cvt_pk_bf16_f32 v218, v192, v193
	v_pk_mul_f32 v[192:193], v[116:117], v[184:185]
	s_nop 0
	v_cvt_pk_bf16_f32 v219, v192, v193
	global_store_dwordx4 v[182:183], v[216:219], off

; __device__ __forceinline__ unsigned cvt_pk_bf16(float lo, float hi) { const f32x2_t v = {lo, hi}; const bf16x2_t b = __builtin_convertvector(v, bf16x2_t); return __builtin_bit_cast(unsigned, b); }
; __device__ __forceinline__ float bf_lo(unsigned w) { return __uint_as_float(w << 16); }
; __device__ __forceinline__ float bf_hi(unsigned w) { return __uint_as_float(w & 0xffff0000u); }
; __device__ __forceinline__ float fast_rcp(float x) { return __builtin_amdgcn_rcpf(x); }
;     __device__ __forceinline__ void operator()(f32x4 (&acc)[2][2][4][2], const Unit& u, int wr, int wc, int fr, int fq) const {
;     ...
;             for (int m = 0; m < 4; ++m) {
;                 const int r = EPI_ROWS(ai, m);
; #pragma unroll
;                 for (int bj = 0; bj < 2; ++bj) {
;                     if (u.seg == 0) {
; #pragma unroll
;                         for (int q = 0; q < 4; ++q) {
;                             const float r0 = bf_lo(ga[m][bj][q]) * fast_rcp(bf_lo(gb[m][bj][q])), r1 = bf_hi(ga[m][bj][q]) * fast_rcp(bf_hi(gb[m][bj][q]));
;                             acc[ai][bj][m][q >> 1][(q & 1) * 2] *= r0; acc[ai][bj][m][q >> 1][(q & 1) * 2 + 1] *= r1;
;                         }
;                     } else {
;                         u32x4 w;
; #pragma unroll
;                         for (int q = 0; q < 4; ++q) {
;                             const float a0 = acc[ai][bj][m][q >> 1][(q & 1) * 2] * bf_lo(gb[m][bj][q]), a1 = acc[ai][bj][m][q >> 1][(q & 1) * 2 + 1] * bf_hi(gb[m][bj][q]);
;                             w[q] = cvt_pk_bf16(a0, a1);
;                         }
;                         *(u32x4*)(Mg + (size_t)r * DM + c0 + 32 * bj) = w;
;                     }
;                 }
.LBB0_750:
	s_mov_b64 s[0:1], -1
	s_and_b64 vcc, exec, s[42:43]
	s_waitcnt vmcnt(4)
	v_lshlrev_b32_e32 v188, 16, v178
	v_and_b32_e32 v189, 0xffff0000, v178
	v_lshlrev_b32_e32 v186, 16, v179
	v_and_b32_e32 v187, 0xffff0000, v179
	v_lshlrev_b32_e32 v184, 16, v180
	v_and_b32_e32 v185, 0xffff0000, v180
	v_lshlrev_b32_e32 v178, 16, v181
	v_and_b32_e32 v179, 0xffff0000, v181
	s_cbranch_vccnz .LBB0_752
	v_pk_mul_f32 v[180:181], v[86:87], v[188:189]
	s_mov_b64 s[0:1], 0
	v_cvt_pk_bf16_f32 v190, v180, v181
	v_pk_mul_f32 v[180:181], v[88:89], v[186:187]
	s_nop 0
	v_cvt_pk_bf16_f32 v191, v180, v181
	v_pk_mul_f32 v[180:181], v[82:83], v[184:185]
	s_nop 0
	v_cvt_pk_bf16_f32 v192, v180, v181
	v_pk_mul_f32 v[180:181], v[84:85], v[178:179]
	s_nop 0
	v_cvt_pk_bf16_f32 v193, v180, v181
	global_store_dwordx4 v[182:183], v[190:193], off offset:64

; __device__ __forceinline__ unsigned cvt_pk_bf16(float lo, float hi) { const f32x2_t v = {lo, hi}; const bf16x2_t b = __builtin_convertvector(v, bf16x2_t); return __builtin_bit_cast(unsigned, b); }
; __device__ __forceinline__ float bf_lo(unsigned w) { return __uint_as_float(w << 16); }
; __device__ __forceinline__ float bf_hi(unsigned w) { return __uint_as_float(w & 0xffff0000u); }
; __device__ __forceinline__ float fast_rcp(float x) { return __builtin_amdgcn_rcpf(x); }
;     __device__ __forceinline__ void operator()(f32x4 (&acc)[2][2][4][2], const Unit& u, int wr, int wc, int fr, int fq) const {
;     ...
;             for (int m = 0; m < 4; ++m) {
;                 const int r = EPI_ROWS(ai, m);
; #pragma unroll
;                 for (int bj = 0; bj < 2; ++bj) {
;                     if (u.seg == 0) {
; #pragma unroll
;                         for (int q = 0; q < 4; ++q) {
;                             const float r0 = bf_lo(ga[m][bj][q]) * fast_rcp(bf_lo(gb[m][bj][q])), r1 = bf_hi(ga[m][bj][q]) * fast_rcp(bf_hi(gb[m][bj][q]));
;                             acc[ai][bj][m][q >> 1][(q & 1) * 2] *= r0; acc[ai][bj][m][q >> 1][(q & 1) * 2 + 1] *= r1;
;                         }
;                     } else {
;                         u32x4 w;
; #pragma unroll
;                         for (int q = 0; q < 4; ++q) {
;                             const float a0 = acc[ai][bj][m][q >> 1][(q & 1) * 2] * bf_lo(gb[m][bj][q]), a1 = acc[ai][bj][m][q >> 1][(q & 1) * 2 + 1] * bf_hi(gb[m][bj][q]);
;                             w[q] = cvt_pk_bf16(a0, a1);
;                         }
;                         *(u32x4*)(Mg + (size_t)r * DM + c0 + 32 * bj) = w;
;                     }
;                 }
.LBB0_754:
	v_add_u32_e32 v178, s2, v224
	v_ashrrev_i32_e32 v179, 31, v178
	v_lshlrev_b64 v[178:179], 11, v[178:179]
	v_lshl_add_u64 v[184:185], s[80:81], 0, v[178:179]
	s_mov_b64 s[0:1], -1
	s_and_b64 vcc, exec, s[42:43]
	s_waitcnt vmcnt(3)
	v_lshlrev_b32_e32 v182, 16, v174
	v_and_b32_e32 v183, 0xffff0000, v174
	v_lshlrev_b32_e32 v180, 16, v175
	v_and_b32_e32 v181, 0xffff0000, v175
	v_lshlrev_b32_e32 v178, 16, v176
	v_and_b32_e32 v179, 0xffff0000, v176
	v_lshlrev_b32_e32 v176, 16, v177
	v_and_b32_e32 v177, 0xffff0000, v177
	v_lshl_add_u64 v[174:175], v[212:213], 1, v[184:185]
	s_cbranch_vccnz .LBB0_756
	v_pk_mul_f32 v[184:185], v[110:111], v[182:183]
	v_pk_mul_f32 v[186:187], v[112:113], v[180:181]
	v_cvt_pk_bf16_f32 v184, v184, v185
	v_cvt_pk_bf16_f32 v185, v186, v187
	v_pk_mul_f32 v[186:187], v[106:107], v[178:179]
	v_pk_mul_f32 v[188:189], v[108:109], v[176:177]
	v_cvt_pk_bf16_f32 v186, v186, v187
	v_cvt_pk_bf16_f32 v187, v188, v189
	s_mov_b64 s[0:1], 0
	global_store_dwordx4 v[174:175], v[184:187], off

; __device__ __forceinline__ unsigned cvt_pk_bf16(float lo, float hi) { const f32x2_t v = {lo, hi}; const bf16x2_t b = __builtin_convertvector(v, bf16x2_t); return __builtin_bit_cast(unsigned, b); }
; __device__ __forceinline__ float bf_lo(unsigned w) { return __uint_as_float(w << 16); }
; __device__ __forceinline__ float bf_hi(unsigned w) { return __uint_as_float(w & 0xffff0000u); }
; __device__ __forceinline__ float fast_rcp(float x) { return __builtin_amdgcn_rcpf(x); }
;     __device__ __forceinline__ void operator()(f32x4 (&acc)[2][2][4][2], const Unit& u, int wr, int wc, int fr, int fq) const {
;     ...
;             for (int m = 0; m < 4; ++m) {
;                 const int r = EPI_ROWS(ai, m);
; #pragma unroll
;                 for (int bj = 0; bj < 2; ++bj) {
;                     if (u.seg == 0) {
; #pragma unroll
;                         for (int q = 0; q < 4; ++q) {
;                             const float r0 = bf_lo(ga[m][bj][q]) * fast_rcp(bf_lo(gb[m][bj][q])), r1 = bf_hi(ga[m][bj][q]) * fast_rcp(bf_hi(gb[m][bj][q]));
;                             acc[ai][bj][m][q >> 1][(q & 1) * 2] *= r0; acc[ai][bj][m][q >> 1][(q & 1) * 2 + 1] *= r1;
;                         }
;                     } else {
;                         u32x4 w;
; #pragma unroll
;                         for (int q = 0; q < 4; ++q) {
;                             const float a0 = acc[ai][bj][m][q >> 1][(q & 1) * 2] * bf_lo(gb[m][bj][q]), a1 = acc[ai][bj][m][q >> 1][(q & 1) * 2 + 1] * bf_hi(gb[m][bj][q]);
;                             w[q] = cvt_pk_bf16(a0, a1);
;                         }
;                         *(u32x4*)(Mg + (size_t)r * DM + c0 + 32 * bj) = w;
;                     }
;                 }
.LBB0_758:
	s_mov_b64 s[0:1], -1
	s_and_b64 vcc, exec, s[42:43]
	s_waitcnt vmcnt(2)
	v_lshlrev_b32_e32 v180, 16, v170
	v_and_b32_e32 v181, 0xffff0000, v170
	v_lshlrev_b32_e32 v178, 16, v171
	v_and_b32_e32 v179, 0xffff0000, v171
	v_lshlrev_b32_e32 v176, 16, v172
	v_and_b32_e32 v177, 0xffff0000, v172
	v_lshlrev_b32_e32 v170, 16, v173
	v_and_b32_e32 v171, 0xffff0000, v173
	s_cbranch_vccnz .LBB0_760
	v_pk_mul_f32 v[172:173], v[78:79], v[180:181]
	s_mov_b64 s[0:1], 0
	v_cvt_pk_bf16_f32 v182, v172, v173
	v_pk_mul_f32 v[172:173], v[80:81], v[178:179]
	s_nop 0
	v_cvt_pk_bf16_f32 v183, v172, v173
	v_pk_mul_f32 v[172:173], v[74:75], v[176:177]
	s_nop 0
	v_cvt_pk_bf16_f32 v184, v172, v173
	v_pk_mul_f32 v[172:173], v[76:77], v[170:171]
	s_nop 0
	v_cvt_pk_bf16_f32 v185, v172, v173
	global_store_dwordx4 v[174:175], v[182:185], off offset:64

; __device__ __forceinline__ unsigned cvt_pk_bf16(float lo, float hi) { const f32x2_t v = {lo, hi}; const bf16x2_t b = __builtin_convertvector(v, bf16x2_t); return __builtin_bit_cast(unsigned, b); }
; __device__ __forceinline__ float bf_lo(unsigned w) { return __uint_as_float(w << 16); }
; __device__ __forceinline__ float bf_hi(unsigned w) { return __uint_as_float(w & 0xffff0000u); }
; __device__ __forceinline__ float fast_rcp(float x) { return __builtin_amdgcn_rcpf(x); }
;     __device__ __forceinline__ void operator()(f32x4 (&acc)[2][2][4][2], const Unit& u, int wr, int wc, int fr, int fq) const {
;     ...
;             for (int m = 0; m < 4; ++m) {
;                 const int r = EPI_ROWS(ai, m);
; #pragma unroll
;                 for (int bj = 0; bj < 2; ++bj) {
;                     if (u.seg == 0) {
; #pragma unroll
;                         for (int q = 0; q < 4; ++q) {
;                             const float r0 = bf_lo(ga[m][bj][q]) * fast_rcp(bf_lo(gb[m][bj][q])), r1 = bf_hi(ga[m][bj][q]) * fast_rcp(bf_hi(gb[m][bj][q]));
;                             acc[ai][bj][m][q >> 1][(q & 1) * 2] *= r0; acc[ai][bj][m][q >> 1][(q & 1) * 2 + 1] *= r1;
;                         }
;                     } else {
;                         u32x4 w;
; #pragma unroll
;                         for (int q = 0; q < 4; ++q) {
;                             const float a0 = acc[ai][bj][m][q >> 1][(q & 1) * 2] * bf_lo(gb[m][bj][q]), a1 = acc[ai][bj][m][q >> 1][(q & 1) * 2 + 1] * bf_hi(gb[m][bj][q]);
;                             w[q] = cvt_pk_bf16(a0, a1);
;                         }
;                         *(u32x4*)(Mg + (size_t)r * DM + c0 + 32 * bj) = w;
;                     }
;                 }
.LBB0_762:
	v_add_u32_e32 v170, s2, v226
	v_ashrrev_i32_e32 v171, 31, v170
	v_lshlrev_b64 v[170:171], 11, v[170:171]
	v_lshl_add_u64 v[176:177], s[80:81], 0, v[170:171]
	s_mov_b64 s[0:1], -1
	s_and_b64 vcc, exec, s[42:43]
	s_waitcnt vmcnt(1)
	v_lshlrev_b32_e32 v174, 16, v166
	v_and_b32_e32 v175, 0xffff0000, v166
	v_lshlrev_b32_e32 v172, 16, v167
	v_and_b32_e32 v173, 0xffff0000, v167
	v_lshlrev_b32_e32 v170, 16, v168
	v_and_b32_e32 v171, 0xffff0000, v168
	v_lshlrev_b32_e32 v168, 16, v169
	v_and_b32_e32 v169, 0xffff0000, v169
	v_lshl_add_u64 v[166:167], v[212:213], 1, v[176:177]
	s_cbranch_vccnz .LBB0_764
	v_pk_mul_f32 v[176:177], v[102:103], v[174:175]
	v_pk_mul_f32 v[178:179], v[104:105], v[172:173]
	v_cvt_pk_bf16_f32 v176, v176, v177
	v_cvt_pk_bf16_f32 v177, v178, v179
	v_pk_mul_f32 v[178:179], v[98:99], v[170:171]
	v_pk_mul_f32 v[180:181], v[100:101], v[168:169]
	v_cvt_pk_bf16_f32 v178, v178, v179
	v_cvt_pk_bf16_f32 v179, v180, v181
	s_mov_b64 s[0:1], 0
	global_store_dwordx4 v[166:167], v[176:179], off

; __device__ __forceinline__ unsigned cvt_pk_bf16(float lo, float hi) { const f32x2_t v = {lo, hi}; const bf16x2_t b = __builtin_convertvector(v, bf16x2_t); return __builtin_bit_cast(unsigned, b); }
; __device__ __forceinline__ float bf_lo(unsigned w) { return __uint_as_float(w << 16); }
; __device__ __forceinline__ float bf_hi(unsigned w) { return __uint_as_float(w & 0xffff0000u); }
; __device__ __forceinline__ float fast_rcp(float x) { return __builtin_amdgcn_rcpf(x); }
;     __device__ __forceinline__ void operator()(f32x4 (&acc)[2][2][4][2], const Unit& u, int wr, int wc, int fr, int fq) const {
;     ...
;             for (int m = 0; m < 4; ++m) {
;                 const int r = EPI_ROWS(ai, m);
; #pragma unroll
;                 for (int bj = 0; bj < 2; ++bj) {
;                     if (u.seg == 0) {
; #pragma unroll
;                         for (int q = 0; q < 4; ++q) {
;                             const float r0 = bf_lo(ga[m][bj][q]) * fast_rcp(bf_lo(gb[m][bj][q])), r1 = bf_hi(ga[m][bj][q]) * fast_rcp(bf_hi(gb[m][bj][q]));
;                             acc[ai][bj][m][q >> 1][(q & 1) * 2] *= r0; acc[ai][bj][m][q >> 1][(q & 1) * 2 + 1] *= r1;
;                         }
;                     } else {
;                         u32x4 w;
; #pragma unroll
;                         for (int q = 0; q < 4; ++q) {
;                             const float a0 = acc[ai][bj][m][q >> 1][(q & 1) * 2] * bf_lo(gb[m][bj][q]), a1 = acc[ai][bj][m][q >> 1][(q & 1) * 2 + 1] * bf_hi(gb[m][bj][q]);
;                             w[q] = cvt_pk_bf16(a0, a1);
;                         }
;                         *(u32x4*)(Mg + (size_t)r * DM + c0 + 32 * bj) = w;
;                     }
;                 }
.LBB0_766:
	s_mov_b64 s[0:1], -1
	s_and_b64 vcc, exec, s[42:43]
	s_waitcnt vmcnt(0)
	v_lshlrev_b32_e32 v172, 16, v162
	v_and_b32_e32 v173, 0xffff0000, v162
	v_lshlrev_b32_e32 v170, 16, v163
	v_and_b32_e32 v171, 0xffff0000, v163
	v_lshlrev_b32_e32 v168, 16, v164
	v_and_b32_e32 v169, 0xffff0000, v164
	v_lshlrev_b32_e32 v162, 16, v165
	v_and_b32_e32 v163, 0xffff0000, v165
	s_cbranch_vccnz .LBB0_768
	v_pk_mul_f32 v[164:165], v[70:71], v[172:173]
	s_mov_b64 s[0:1], 0
	v_cvt_pk_bf16_f32 v174, v164, v165
	v_pk_mul_f32 v[164:165], v[72:73], v[170:171]
	s_nop 0
	v_cvt_pk_bf16_f32 v175, v164, v165
	v_pk_mul_f32 v[164:165], v[66:67], v[168:169]
	s_nop 0
	v_cvt_pk_bf16_f32 v176, v164, v165
	v_pk_mul_f32 v[164:165], v[68:69], v[162:163]
	s_nop 0
	v_cvt_pk_bf16_f32 v177, v164, v165
	global_store_dwordx4 v[166:167], v[174:177], off offset:64
